# x to bf16 conversion (layer-0 conv phase): all eight row-piece loads issued up front, waits counted vmcnt(7) instead of a load/store/vmcnt(0) ladder (on top of v31)
# speedup vs baseline: 1.0019x; 1.0019x over previous
; __device__ __forceinline__ float wave_sum(float v) { v = allreduce16(v); v += swz16(v); return sum32(v); }
; __device__ __forceinline__ void phase_conv(PC p, int wv, int L, LAS unsigned char* lds, int part) {
;     ...
;             const int row = (it - nW - nPad - nP) * 8 + (tid >> 6), lane = tid & 63;
;             const float* s = p->x + (size_t)row * DM; u16* d = p->mix + (size_t)row * DM;
;             float sq = 0.f;
; #pragma unroll
;             for (int i = 0; i < 8; ++i) {
;                 const float4 v = *(const float4*)(s + (i * 64 + lane) * 4);
;                 sq += v.x * v.x + v.y * v.y + v.z * v.z + v.w * v.w;
;                 u32x2 o; o.x = pack2(v.x, v.y); o.y = pack2(v.z, v.w);
;                 *(u32x2*)(d + (i * 64 + lane) * 4) = o;
;             }
;             sq = wave_sum(sq);
;             if (lane < 32) p->ss0[(size_t)row * 32 + lane] = (lane == 0) ? sq : 0.f;
.LBB0_38:
	s_add_i32 s16, s12, 0x1100
	s_cmpk_gt_i32 s16, 0x10ff
	s_mov_b64 s[10:11], -1
	s_cbranch_scc0 .LBB0_46
	s_cmpk_gt_u32 s16, 0x14ff
	s_cbranch_scc0 .LBB0_43
	s_load_dwordx2 s[10:11], s[8:9], 0x0
	s_load_dwordx2 s[16:17], s[8:9], 0x110
	v_ashrrev_i32_e32 v7, 31, v6
	v_lshlrev_b64 v[24:25], 13, v[6:7]
	v_lshlrev_b64 v[28:29], 12, v[6:7]
	s_waitcnt lgkmcnt(0)
	v_lshl_add_u64 v[52:53], s[10:11], 0, v[24:25]
	v_lshl_add_u64 v[36:37], v[52:53], 0, v[2:3]
	global_load_dwordx4 v[24:27], v[36:37], off
	v_mov_b32_e32 v11, v3
	v_lshl_add_u64 v[28:29], s[16:17], 0, v[28:29]
	v_lshl_add_u64 v[56:57], v[28:29], 0, v[10:11]
	v_mov_b32_e32 v13, v3
	v_lshl_add_u64 v[40:41], v[52:53], 0, v[12:13]
	v_mov_b32_e32 v15, v3
	v_lshl_add_u64 v[44:45], v[52:53], 0, v[14:15]
	v_mov_b32_e32 v17, v3
	v_lshl_add_u64 v[48:49], v[52:53], 0, v[16:17]
	v_mov_b32_e32 v19, v3
	v_lshl_add_u64 v[52:53], v[52:53], 0, v[18:19]
	global_load_dwordx4 v[60:63], v[36:37], off offset:1024
	global_load_dwordx4 v[64:67], v[36:37], off offset:2048
	global_load_dwordx4 v[68:71], v[36:37], off offset:3072
	global_load_dwordx4 v[72:75], v[40:41], off
	global_load_dwordx4 v[76:79], v[44:45], off
	global_load_dwordx4 v[80:83], v[48:49], off
	global_load_dwordx4 v[84:87], v[52:53], off
	s_waitcnt vmcnt(7)
	v_cvt_pk_bf16_f32 v28, v24, v25
	v_cvt_pk_bf16_f32 v29, v26, v27
	global_store_dwordx2 v[56:57], v[28:29], off
	v_mul_f32_e32 v9, v25, v25
	v_fmac_f32_e32 v9, v24, v24
	v_fmac_f32_e32 v9, v26, v26
	v_fmac_f32_e32 v9, v27, v27
	s_waitcnt vmcnt(7)
	v_cvt_pk_bf16_f32 v32, v60, v61
	v_cvt_pk_bf16_f32 v33, v62, v63
	global_store_dwordx2 v[56:57], v[32:33], off offset:512
	v_mul_f32_e32 v11, v61, v61
	v_fmac_f32_e32 v11, v60, v60
	v_fmac_f32_e32 v11, v62, v62
	v_fmac_f32_e32 v11, v63, v63
	v_add_f32_e32 v9, v9, v11
	s_waitcnt vmcnt(7)
	v_cvt_pk_bf16_f32 v38, v64, v65
	v_cvt_pk_bf16_f32 v39, v66, v67
	global_store_dwordx2 v[56:57], v[38:39], off offset:1024
	v_mul_f32_e32 v11, v65, v65
	v_fmac_f32_e32 v11, v64, v64
	v_fmac_f32_e32 v11, v66, v66
	v_fmac_f32_e32 v11, v67, v67
	v_add_f32_e32 v9, v9, v11
	s_waitcnt vmcnt(7)
	v_cvt_pk_bf16_f32 v42, v68, v69
	v_cvt_pk_bf16_f32 v43, v70, v71
	global_store_dwordx2 v[56:57], v[42:43], off offset:1536
	v_mul_f32_e32 v11, v69, v69
	v_fmac_f32_e32 v11, v68, v68
	v_fmac_f32_e32 v11, v70, v70
	v_fmac_f32_e32 v11, v71, v71
	v_add_f32_e32 v9, v9, v11
	s_waitcnt vmcnt(7)
	v_cvt_pk_bf16_f32 v46, v72, v73
	v_cvt_pk_bf16_f32 v47, v74, v75
	global_store_dwordx2 v[56:57], v[46:47], off offset:2048
	v_mul_f32_e32 v11, v73, v73
	v_fmac_f32_e32 v11, v72, v72
	v_fmac_f32_e32 v11, v74, v74
	v_fmac_f32_e32 v11, v75, v75
	v_add_f32_e32 v9, v9, v11
	s_waitcnt vmcnt(7)
	v_cvt_pk_bf16_f32 v50, v76, v77
	v_cvt_pk_bf16_f32 v51, v78, v79
	global_store_dwordx2 v[56:57], v[50:51], off offset:2560
	v_mul_f32_e32 v11, v77, v77
	v_fmac_f32_e32 v11, v76, v76
	v_fmac_f32_e32 v11, v78, v78
	v_fmac_f32_e32 v11, v79, v79
	v_add_f32_e32 v9, v9, v11
	s_waitcnt vmcnt(7)
	v_cvt_pk_bf16_f32 v54, v80, v81
	v_cvt_pk_bf16_f32 v55, v82, v83
	global_store_dwordx2 v[56:57], v[54:55], off offset:3072
	v_mul_f32_e32 v11, v81, v81
	v_fmac_f32_e32 v11, v80, v80
	v_fmac_f32_e32 v11, v82, v82
	v_fmac_f32_e32 v11, v83, v83
	v_add_f32_e32 v9, v9, v11
	s_waitcnt vmcnt(7)
	v_mul_f32_e32 v11, v85, v85
	v_fmac_f32_e32 v11, v84, v84
	v_fmac_f32_e32 v11, v86, v86
	v_fmac_f32_e32 v11, v87, v87
	v_add_f32_e32 v9, v9, v11
	v_cvt_pk_bf16_f32 v24, v84, v85
	v_cvt_pk_bf16_f32 v25, v86, v87
	v_add_f32_dpp v9, v9, v9 quad_perm:[1,0,3,2] row_mask:0xf bank_mask:0xf bound_ctrl:1
	global_store_dwordx2 v[56:57], v[24:25], off offset:3584
	s_nop 0
	v_add_f32_dpp v9, v9, v9 quad_perm:[2,3,0,1] row_mask:0xf bank_mask:0xf bound_ctrl:1
	s_nop 1
	v_add_f32_dpp v9, v9, v9 row_half_mirror row_mask:0xf bank_mask:0xf bound_ctrl:1
	s_nop 1
	v_add_f32_dpp v9, v9, v9 row_mirror row_mask:0xf bank_mask:0xf bound_ctrl:1
	ds_swizzle_b32 v11, v9 offset:swizzle(SWAP,16)
	s_waitcnt lgkmcnt(0)
	v_add_f32_e32 v9, v9, v11
	v_mov_b32_e32 v11, v9
	s_nop 1
	v_permlane32_swap_b32_e32 v9, v11
	s_and_saveexec_b64 s[10:11], s[4:5]
	s_cbranch_execz .LBB0_42
	v_add_f32_e32 v9, v9, v11
	v_lshlrev_b64 v[24:25], 7, v[6:7]
	v_cndmask_b32_e64 v9, 0, v9, s[6:7]
	v_lshl_add_u64 v[24:25], v[4:5], 0, v[24:25]
	global_store_dword v[24:25], v9, off
